# back-off release poll: s_sleep 1 -> s_sleep 3 in waiter XGEN poll loop (same size, offsets unchanged)
# speedup vs baseline: 1.0056x; 1.0056x over previous
; __device__ __forceinline__ unsigned xb_ld(unsigned* p)              { return __hip_atomic_load(p, __ATOMIC_RELAXED, __HIP_MEMORY_SCOPE_AGENT); }
; #define XB_SPIN(cond, bar) do { unsigned _sp = 0; while (cond) { __builtin_amdgcn_s_sleep(1); \
;     if ((++_sp & 255u) == 0u) { if (xb_ld(&(bar)[XB_TMO])) break; if (_sp > XB_SPIN_CAP) { atomicAdd(&(bar)[XB_TMO], 1u); break; } } } } while (0)
; __device__ __forceinline__ void xcd_barrier(const XcdBarrier& b) {
;     ...
;     } else {
;       XB_SPIN(xb_ld(&bar[XB_XGEN(b.x)]) == gen, bar);
;       __builtin_amdgcn_fence(__ATOMIC_ACQUIRE, "agent");
;       asm volatile("s_waitcnt vmcnt(0)" ::: "memory");
;     }
.LBB0_36:
	s_and_b32 s34, s4, 0xff
	s_mov_b64 s[94:95], -1
	s_cmp_lg_u32 s34, 0
	s_mov_b64 vcc, -1
	s_sleep 3
	s_cbranch_scc0 .LBB0_39
	s_and_b64 vcc, exec, vcc
	s_cbranch_vccz .LBB0_35
